# P1 full-line store transform + LRU ya output via LDS tile and full-line dwordx4 stores
# baseline (speedup 1.0000x reference)
; #define GAS __attribute__((address_space(1)))
; #define LAS __attribute__((address_space(3)))
; __device__ __forceinline__ void lru_unit(Frame& F, int seq, int n) {
;     const bool smp = seq >= 32; const int b = smp ? seq - 32 : seq; const int T = smp ? DSEQ : SEQ;
;     const size_t rowbase = smp ? (size_t)MP + (size_t)b * DSEQ : (size_t)b * SEQ;
;     int tid = F.tid; asm volatile("" : "+v"(tid));
;     const int lane = tid & 63, w = F.wave;
;     LAS unsigned char* L = F.lds;
;     LAS bf16* XCB = (LAS bf16*)(L + L_XCB); LAS bf16* RAW = (LAS bf16*)(L + L_RAW); LAS bf16* HALO = (LAS bf16*)(L + L_HALO); LAS float* BB = (LAS float*)(L + L_BB);
;     const bf16* XA = (const bf16*)(F.ws + WS_XA); const bf16* ZA = (const bf16*)(F.ws + WS_ZA); bf16* YAB = (bf16*)(F.ws + WS_YAB);
;     const int ct = tid >> 4, cg = tid & 15, c0 = 128 * n + 8 * cg;
;     float cw[4][8], cbias[8];
; #pragma unroll
;     for (int e = 0; e < 8; ++e) { cbias[e] = F.in[9][c0 + e];
; #pragma unroll
;         for (int j = 0; j < 4; ++j) cw[j][e] = F.in[8][j * DM + c0 + e]; }
;     const int dl = 16 * w + (lane & 15), tq = lane >> 4, dg = 128 * n + dl;
;     const float brg = F.in[11][dg], big = F.in[13][dg];
;     float nsp; { const float x = -F.in[14][dg]; const float sp = fmaxf(x, 0.f) + log1pf(expf(-fabsf(x))); nsp = -8.f * LOG2E * sp; }
;     bf16x8 Br[4], Bi[4];
;     { const bf16* WG = (const bf16*)(F.ws + WS_WG) + (size_t)(2 * n) * 16384;
; #pragma unroll
;       for (int kk = 0; kk < 4; ++kk) { Br[kk] = *(const GAS bf16x8*)(WG + (size_t)dl * 128 + 32 * kk + 8 * tq); Bi[kk] = *(const GAS bf16x8*)(WG + 16384 + (size_t)dl * 128 + 32 * kk + 8 * tq); } }
;     float hc = smp ? F.in[5][b * DM + dg] : 0.f;
;     ...
;     if (tq == 0) F.out[(smp ? O_LS : O_LP) + (size_t)b * DM + dg] = hc;
;     __syncthreads();
; }
.LBB0_422:
	s_or_b64 exec, exec, s[0:1]
	s_cmpk_gt_i32 s96, 0x1ff
	s_waitcnt lgkmcnt(0)
	s_barrier
	s_cbranch_scc1 .LBB0_444
	v_and_b32_e32 v220, 63, v0
	v_lshrrev_b32_e32 v221, 4, v220
	v_and_b32_e32 v222, 15, v220
	v_mul_u32_u24_e32 v221, 0x440, v221
	v_lshlrev_b32_e32 v222, 1, v222
	s_lshl_b32 s92, s97, 5
	v_add3_u32 v217, v221, v222, s92
	v_add_u32_e32 v217, 0x12000, v217
	v_lshrrev_b32_e32 v221, 4, v0
	v_and_b32_e32 v222, 15, v0
	v_lshlrev_b32_e32 v218, 12, v221
	v_lshl_or_b32 v218, v222, 4, v218
	v_mul_u32_u24_e32 v219, 0x110, v221
	v_lshl_add_u32 v219, v222, 4, v219
	v_add_u32_e32 v219, 0x12000, v219
	v_add_u32_e32 v3, -16, v2
	v_cmp_lt_i32_e32 vcc, v3, v121
	s_add_u32 s10, s74, 0xa400000
	s_addc_u32 s11, s75, 0
	v_cndmask_b32_e32 v3, v3, v2, vcc
	v_lshlrev_b32_e32 v124, 2, v3
	v_subrev_u32_e32 v3, 32, v2
	s_add_u32 s28, s74, 0x12800000
	v_cmp_lt_i32_e32 vcc, v3, v121
	s_addc_u32 s29, s75, 0
	s_lshl_b32 s3, s97, 4
	v_cndmask_b32_e32 v2, v3, v2, vcc
	s_add_u32 s12, s74, 0x1800000
	v_lshlrev_b32_e32 v125, 2, v2
	s_addc_u32 s13, s75, 0
	s_mov_b32 s31, 0
	v_mov_b32_e32 v115, 0
	s_movk_i32 s14, 0x110
	s_mov_b32 s15, 0xbfb8aa3b
	s_mov_b32 s34, 0xc2b17218
	s_mov_b32 s35, 0x7f800000
	s_mov_b32 s50, 0x3f2aaaab
	v_mov_b32_e32 v126, 0x3ecc95a3
	s_mov_b32 s51, 0x3f317218
	s_mov_b32 s56, 0x33800000
	s_mov_b32 s57, 0x10000
	s_mov_b32 s60, 0x9000
	s_mov_b32 s61, 0x11000
	s_mov_b32 s66, 0x18000
	s_mov_b32 s67, 0x19000
	s_movk_i32 s68, 0x210
	s_movk_i32 s69, 0xffe2
	s_movk_i32 s70, 0xffe1
	s_movk_i32 s71, 0xffe0
	s_movk_i32 s76, 0xffdf
	s_mov_b32 s77, 0x4c401000
	s_mov_b32 s78, 0x4c403000
	s_mov_b32 s79, 0x4c411000
	s_mov_b32 s80, 0x4c413000
	s_mov_b32 s81, 0x4c421000
	s_mov_b32 s82, 0x4c423000
	s_mov_b32 s83, 0x4c431000
	s_mov_b32 s84, 0x4c432000
	s_mov_b32 s85, 0x30860000
	v_mov_b32_e32 v127, 0x7f800000
	v_mov_b32_e32 v128, 0x8800
	v_mov_b32_e32 v129, 0x40d0
	v_mov_b32_e32 v130, 0x8910
	v_mov_b32_e32 v131, 0x41e0
	v_mov_b32_e32 v132, 0x8a20
	v_mov_b32_e32 v133, 0x42f0
	v_mov_b32_e32 v134, 0x4400
	v_mov_b32_e32 v135, 0x8b30
	v_mov_b32_e32 v136, 0xab10
	v_mov_b32_e32 v137, 0x63e0
	v_mov_b32_e32 v138, 0xac20
	v_mov_b32_e32 v139, 0x64f0
	v_mov_b32_e32 v140, 0xad30
	v_mov_b32_e32 v141, 0x6600
	v_mov_b32_e32 v142, 0xc0
	s_mov_b32 s86, s96
	s_mov_b32 s87, s96
	s_branch .LBB0_425
.LBB0_424:
	s_or_b64 exec, exec, s[0:1]
	s_add_i32 s87, s33, s87
	s_add_i32 s86, s86, s33
	s_waitcnt lgkmcnt(0)
	s_barrier
	ds_read_b128 v[220:223], v219
	ds_read_b128 v[224:227], v219 offset:8704
	s_add_u32 s98, s92, 0x20000
	s_addc_u32 s99, s93, 0
	s_waitcnt lgkmcnt(0)
	global_store_dwordx4 v218, v[220:223], s[92:93]
	global_store_dwordx4 v218, v[224:227], s[98:99]
	s_cmpk_gt_i32 s87, 0x1ff
	s_cbranch_scc1 .LBB0_444

; #define GAS __attribute__((address_space(1)))
; #define LAS __attribute__((address_space(3)))
; __device__ __forceinline__ v4u pack8(const float* v) { v4u w; w.x = pk2(v[0], v[1]); w.y = pk2(v[2], v[3]); w.z = pk2(v[4], v[5]); w.w = pk2(v[6], v[7]); return w; }
; __device__ __forceinline__ void lru_unit(Frame& F, int seq, int n) {
;     ...
;     const int dl = 16 * w + (lane & 15), tq = lane >> 4, dg = 128 * n + dl;
;     const float brg = F.in[11][dg], big = F.in[13][dg];
;     float nsp; { const float x = -F.in[14][dg]; const float sp = fmaxf(x, 0.f) + log1pf(expf(-fabsf(x))); nsp = -8.f * LOG2E * sp; }
;     bf16x8 Br[4], Bi[4];
;     { const bf16* WG = (const bf16*)(F.ws + WS_WG) + (size_t)(2 * n) * 16384;
; #pragma unroll
;       for (int kk = 0; kk < 4; ++kk) { Br[kk] = *(const GAS bf16x8*)(WG + (size_t)dl * 128 + 32 * kk + 8 * tq); Bi[kk] = *(const GAS bf16x8*)(WG + 16384 + (size_t)dl * 128 + 32 * kk + 8 * tq); } }
;     float hc = smp ? F.in[5][b * DM + dg] : 0.f;
;     if (tid < 48) { const int hr = tid >> 4; float x[8];
;         if (smp) { const GAS f32x4* sp_ = (const GAS f32x4*)(F.in[4] + (size_t)(b * 3 + hr) * DM + c0); const f32x4 s0 = sp_[0], s1 = sp_[1];
;             x[0] = s0.x; x[1] = s0.y; x[2] = s0.z; x[3] = s0.w; x[4] = s1.x; x[5] = s1.y; x[6] = s1.z; x[7] = s1.w; }
;         else {
; #pragma unroll
;             for (int e = 0; e < 8; ++e) x[e] = 0.f; }
;         *(LAS v4u*)(HALO + hr * 136 + 8 * cg) = pack8(x); }
;     v4u xr0, xr1; unsigned short zc[16], zn[16];
;     const bf16* xsrc = XA + (rowbase + ct) * DM + c0; const bf16* zsrc = ZA + (rowbase + 4 * tq) * DM + dg;
;     xr0 = *(const GAS v4u*)(xsrc); xr1 = *(const GAS v4u*)(xsrc + (size_t)32 * DM);
; #pragma unroll
;     for (int i = 0; i < 16; ++i) zc[i] = *(const GAS unsigned short*)(zsrc + (size_t)(16 * (i >> 2) + (i & 3)) * DM);
.LBB0_437:
	s_or_b64 exec, exec, s[4:5]
	s_waitcnt vmcnt(9)
	v_mul_f32_e64 v74, |v85|, s15
	v_rndne_f32_e32 v75, v74
	v_sub_f32_e32 v76, v74, v75
	v_fma_f32 v74, |v85|, s15, -v74
	s_mov_b32 s0, 0xb2a5705f
	v_fma_f32 v74, |v85|, s0, v74
	v_add_f32_e32 v74, v76, v74
	v_exp_f32_e32 v74, v74
	v_cvt_i32_f32_e32 v75, v75
	s_mov_b32 s0, 0x42ce8ed0
	v_cmp_ngt_f32_e64 vcc, |v85|, s0
	v_max_f32_e64 v76, -v85, -v85
	v_ldexp_f32 v74, v74, v75
	v_cndmask_b32_e32 v74, 0, v74, vcc
	v_cmp_nlt_f32_e64 vcc, |v85|, s34
	v_max_f32_e32 v100, 0, v76
	s_movk_i32 s0, 0x1000
	v_cndmask_b32_e32 v101, v127, v74, vcc
	v_add_f32_e32 v76, 1.0, v101
	v_add_f32_e32 v74, -1.0, v76
	v_sub_f32_e32 v75, v74, v76
	v_add_f32_e32 v75, 1.0, v75
	v_sub_f32_e32 v74, v101, v74
	v_add_f32_e32 v77, v74, v75
	v_frexp_mant_f32_e32 v78, v76
	v_cvt_f64_f32_e32 v[74:75], v76
	v_frexp_exp_i32_f64_e32 v74, v[74:75]
	v_cmp_gt_f32_e32 vcc, s50, v78
	v_add_u32_e32 v151, 0x2200, v83
	v_cmp_eq_u32_e64 s[4:5], 0, v91
	v_subbrev_co_u32_e32 v74, vcc, 0, v74, vcc
	v_sub_u32_e32 v75, 0, v74
	v_ldexp_f32 v76, v76, v75
	v_ldexp_f32 v75, v77, v75
	v_add_f32_e32 v77, -1.0, v76
	v_add_f32_e32 v80, 1.0, v76
	v_add_f32_e32 v78, 1.0, v77
	v_add_f32_e32 v81, -1.0, v80
	v_sub_f32_e32 v78, v76, v78
	v_sub_f32_e32 v76, v76, v81
	v_add_f32_e32 v78, v75, v78
	v_add_f32_e32 v75, v75, v76
	v_add_f32_e32 v76, v80, v75
	v_rcp_f32_e32 v81, v76
	v_add_f32_e32 v79, v77, v78
	v_sub_f32_e32 v77, v77, v79
	v_add_f32_e32 v77, v78, v77
	v_sub_f32_e32 v78, v80, v76
	v_add_f32_e32 v75, v75, v78
	v_mul_f32_e32 v78, v79, v81
	v_mul_f32_e32 v80, v76, v78
	v_fma_f32 v85, v78, v76, -v80
	v_fmac_f32_e32 v85, v78, v75
	v_add_f32_e32 v86, v80, v85
	v_sub_f32_e32 v87, v79, v86
	v_sub_f32_e32 v79, v79, v87
	v_sub_f32_e32 v80, v86, v80
	v_sub_f32_e32 v79, v79, v86
	v_add_f32_e32 v77, v77, v79
	v_sub_f32_e32 v79, v80, v85
	v_add_f32_e32 v77, v79, v77
	v_add_f32_e32 v79, v87, v77
	v_mul_f32_e32 v80, v81, v79
	v_mul_f32_e32 v85, v76, v80
	v_fma_f32 v76, v80, v76, -v85
	v_fmac_f32_e32 v76, v80, v75
	v_sub_f32_e32 v75, v87, v79
	v_add_f32_e32 v75, v77, v75
	v_add_f32_e32 v77, v85, v76
	v_sub_f32_e32 v86, v79, v77
	v_sub_f32_e32 v79, v79, v86
	v_sub_f32_e32 v85, v77, v85
	v_sub_f32_e32 v77, v79, v77
	v_add_f32_e32 v75, v75, v77
	v_sub_f32_e32 v76, v85, v76
	v_cvt_f32_i32_e32 v74, v74
	v_add_f32_e32 v75, v76, v75
	v_add_f32_e32 v76, v78, v80
	v_add_f32_e32 v75, v86, v75
	v_sub_f32_e32 v77, v76, v78
	v_mul_f32_e32 v75, v81, v75
	v_sub_f32_e32 v77, v80, v77
	v_add_f32_e32 v75, v77, v75
	v_mul_f32_e32 v80, 0x3f317218, v74
	v_add_f32_e32 v77, v76, v75
	v_fma_f32 v81, v74, s51, -v80
	v_mul_f32_e32 v78, v77, v77
	v_fmac_f32_e32 v81, 0xb102e308, v74
	v_fmamk_f32 v79, v78, 0x3e9b6dac, v126
	v_sub_f32_e32 v74, v77, v76
	v_add_f32_e32 v102, v80, v81
	v_fmaak_f32 v79, v78, v79, 0x3f2aaada
	v_sub_f32_e32 v74, v75, v74
	v_sub_f32_e32 v75, v102, v80
	v_mul_f32_e32 v76, v77, v78
	v_sub_f32_e32 v103, v81, v75
	v_ldexp_f32 v75, v77, 1
	v_mul_f32_e32 v76, v76, v79
	v_add_f32_e32 v77, v75, v76
	v_sub_f32_e32 v75, v77, v75
	v_ldexp_f32 v74, v74, 1
	v_sub_f32_e32 v75, v76, v75
	v_add_f32_e32 v74, v74, v75
	v_add_f32_e32 v104, v77, v74
	v_sub_f32_e32 v75, v104, v77
	v_ashrrev_i32_e32 v85, 31, v84
	v_sub_f32_e32 v105, v74, v75
	v_lshl_add_u64 v[74:75], s[44:45], 0, v[84:85]
	v_lshlrev_b64 v[74:75], 11, v[74:75]
	v_lshl_add_u64 v[74:75], s[10:11], 0, v[74:75]
	v_lshlrev_b32_e32 v76, 1, v92
	v_mov_b32_e32 v77, v115
	v_lshl_add_u64 v[116:117], v[74:75], 0, v[76:77]
	v_lshlrev_b32_e32 v74, 2, v91
	v_mov_b32_e32 v75, v115
	v_lshl_add_u64 v[74:75], s[44:45], 0, v[74:75]
	v_lshlrev_b64 v[74:75], 11, v[74:75]
	v_lshl_add_u64 v[74:75], s[28:29], 0, v[74:75]
	v_lshlrev_b32_e32 v76, 1, v114
	v_add_co_u32_e32 v78, vcc, s57, v116
	v_lshl_add_u64 v[118:119], v[74:75], 0, v[76:77]
	s_nop 0
	v_addc_co_u32_e32 v79, vcc, 0, v117, vcc
	v_add_co_u32_e32 v86, vcc, s0, v118
	s_mov_b32 s0, 0x8000
	s_nop 0
	v_addc_co_u32_e32 v87, vcc, 0, v119, vcc
	v_add_co_u32_e32 v92, vcc, s0, v118
	global_load_dwordx4 v[74:77], v[116:117], off
	global_load_ushort v176, v[118:119], off
	global_load_ushort v173, v[118:119], off offset:2048
	v_addc_co_u32_e32 v93, vcc, 0, v119, vcc
	v_add_co_u32_e32 v94, vcc, s60, v118
	global_load_dwordx4 v[78:81], v[78:79], off
	s_nop 0
	global_load_ushort v177, v[86:87], off
	global_load_ushort v174, v[86:87], off offset:2048
	global_load_ushort v167, v[92:93], off offset:2048
	v_addc_co_u32_e32 v95, vcc, 0, v119, vcc
	v_add_co_u32_e32 v86, vcc, s57, v118
	v_add_f32_e32 v106, v102, v104
	s_nop 0
	v_addc_co_u32_e32 v87, vcc, 0, v119, vcc
	v_add_co_u32_e32 v92, vcc, s61, v118
	v_sub_f32_e32 v107, v106, v102
	s_nop 0
	v_addc_co_u32_e32 v93, vcc, 0, v119, vcc
	v_add_co_u32_e32 v96, vcc, s66, v118
	v_sub_f32_e32 v108, v106, v107
	s_nop 0
	v_addc_co_u32_e32 v97, vcc, 0, v119, vcc
	v_add_co_u32_e32 v98, vcc, s67, v118
	v_sub_f32_e32 v85, v102, v108
	s_nop 0
	v_addc_co_u32_e32 v99, vcc, 0, v119, vcc
	global_load_ushort v178, v[94:95], off offset:-4096
	global_load_ushort v175, v[94:95], off
	global_load_ushort v172, v[94:95], off offset:2048
	global_load_ushort v168, v[92:93], off offset:-4096
	global_load_ushort v166, v[86:87], off offset:2048
	global_load_ushort v165, v[92:93], off
	global_load_ushort v161, v[92:93], off offset:2048
	global_load_ushort v154, v[96:97], off offset:2048
	global_load_ushort v159, v[98:99], off offset:-4096
	global_load_ushort v152, v[98:99], off
	global_load_ushort v150, v[98:99], off offset:2048
	v_sub_f32_e32 v86, v104, v107
	v_add_f32_e32 v85, v86, v85
	v_add_f32_e32 v86, v103, v105
	v_sub_f32_e32 v87, v86, v103
	v_sub_f32_e32 v92, v86, v87
; #define GAS __attribute__((address_space(1)))
; #define LAS __attribute__((address_space(3)))
; __device__ __forceinline__ void lru_unit(Frame& F, int seq, int n) {
;     ...
;     for (int t0 = 0; t0 < T; t0 += 64) {
;         *(LAS v4u*)(RAW + ct * 136 + 8 * cg) = xr0; *(LAS v4u*)(RAW + (ct + 32) * 136 + 8 * cg) = xr1;
;         { const int tn = (t0 + 64 < T) ? t0 + 64 : t0;
;           xr0 = *(const GAS v4u*)(xsrc + (size_t)tn * DM); xr1 = *(const GAS v4u*)(xsrc + (size_t)(tn + 32) * DM);
; #pragma unroll
;           for (int i = 0; i < 16; ++i) zn[i] = *(const GAS unsigned short*)(zsrc + (size_t)(tn + 16 * (i >> 2) + (i & 3)) * DM); }
;         __syncthreads();
;     ...
;             const size_t r0 = rowbase + t0 + 4 * tq;
	v_add_f32_e32 v85, v86, v85
	v_sub_f32_e32 v92, v103, v92
	v_sub_f32_e32 v87, v105, v87
	v_add_f32_e32 v86, v106, v85
	v_add_f32_e32 v87, v87, v92
	v_sub_f32_e32 v92, v86, v106
	v_sub_f32_e32 v85, v85, v92
	v_add_f32_e32 v85, v87, v85
	v_add_f32_e32 v85, v86, v85
	v_cmp_neq_f32_e32 vcc, s35, v101
	v_add_u32_e32 v86, 0, v145
	v_lshl_add_u32 v92, v82, 2, 0
	v_cndmask_b32_e32 v85, v127, v85, vcc
	v_cmp_lt_f32_e64 vcc, |v101|, s56
	v_add_u32_e32 v82, 0, v151
	s_and_b32 s0, s86, 7
	v_cndmask_b32_e32 v85, v85, v101, vcc
	v_add_f32_e32 v85, v100, v85
	v_mul_f32_e32 v147, 0xc138aa3b, v85
	v_lshlrev_b32_e32 v85, 1, v90
	v_cmp_lt_i32_e32 vcc, 2, v84
	v_add3_u32 v148, 0, v83, v85
	s_lshl_b32 s2, s0, 7
	v_cndmask_b32_e32 v83, v128, v129, vcc
	v_cmp_lt_i32_e32 vcc, 1, v84
	v_add3_u32 v153, v86, v83, v85
	s_lshl_b64 s[0:1], s[44:45], 12
	v_cndmask_b32_e32 v83, v130, v131, vcc
	v_cmp_lt_i32_e32 vcc, 0, v84
	v_add3_u32 v155, v86, v83, v85
	v_lshl_add_u32 v87, v90, 2, 0
	v_cndmask_b32_e32 v83, v132, v133, vcc
	v_cmp_gt_i32_e32 vcc, 0, v84
	v_add3_u32 v156, v86, v83, v85
	v_sub_u32_e32 v149, v87, v85
	v_cndmask_b32_e32 v83, v134, v135, vcc
	v_cmp_lt_i32_e32 vcc, s69, v84
	v_add3_u32 v157, v86, v83, v85
	v_mul_lo_u32 v93, v84, s68
	v_cndmask_b32_e32 v83, v128, v129, vcc
	v_cmp_lt_i32_e32 vcc, s70, v84
	v_add3_u32 v158, v82, v83, v85
	v_mov_b32_e32 v83, v115
	v_cndmask_b32_e32 v82, v136, v137, vcc
	v_cmp_lt_i32_e32 vcc, s71, v84
	v_add3_u32 v160, v86, v82, v85
	v_lshl_add_u32 v90, v91, 4, 0
	v_cndmask_b32_e32 v82, v138, v139, vcc
	v_cmp_lt_i32_e32 vcc, s76, v84
	v_add3_u32 v162, v86, v82, v85
	v_cmp_lt_u32_e64 s[6:7], 1, v91
	v_cndmask_b32_e32 v82, v140, v141, vcc
	v_add3_u32 v163, v86, v82, v85
	v_or_b32_e32 v82, v89, v121
	v_lshl_or_b32 v164, v82, 2, v142
	v_lshlrev_b32_e32 v82, 8, v88
	v_and_b32_e32 v120, 0x3000, v82
	v_lshlrev_b32_e32 v82, 10, v88
	v_and_b32_e32 v82, 0xc000, v82
	v_lshl_add_u64 v[82:83], v[82:83], 0, s[0:1]
	s_add_i32 s0, s3, s2
	v_add_u32_e32 v84, s0, v89
	v_mov_b32_e32 v85, v115
	v_mul_u32_u24_e32 v94, 0x110, v89
	v_mul_u32_u24_e32 v91, 0x840, v91
	v_lshl_add_u64 v[82:83], v[84:85], 1, v[82:83]
	s_mov_b32 s37, 0
	v_lshl_add_u64 v[122:123], s[74:75], 0, v[82:83]
	s_mov_b64 s[0:1], 0
	v_readfirstlane_b32 s90, v122
	v_readfirstlane_b32 s91, v123
	s_lshl_b32 s92, s97, 5
	s_nop 1
	s_sub_u32 s90, s90, s92
	s_subb_u32 s91, s91, 0
	s_add_u32 s90, s90, 0x4c3c0000
	s_addc_u32 s91, s91, 0
	v_add_u32_e32 v169, v87, v93
	v_add_u32_e32 v170, v90, v94
	v_add_u32_e32 v171, v92, v91
.LBB0_438:
	s_cmpk_lt_u32 s37, 0x7c0
	s_cselect_b64 s[44:45], -1, 0
	s_and_b64 s[46:47], s[40:41], s[44:45]
	s_mov_b32 s2, s37
	s_xor_b64 s[44:45], s[46:47], -1
	s_add_i32 s37, s37, 64
	s_and_b64 s[46:47], s[46:47], exec
	s_cselect_b32 s30, s37, s2
	s_lshl_b64 s[46:47], s[30:31], 11
	s_waitcnt vmcnt(17)
	ds_write_b128 v148, v[74:77] offset:17408
	s_waitcnt vmcnt(14)
	ds_write_b128 v148, v[78:81] offset:26112
	v_lshl_add_u64 v[74:75], v[116:117], 0, s[46:47]
	v_lshl_add_u64 v[82:83], v[118:119], 0, s[46:47]
	s_or_b32 s46, s30, 1
	s_mov_b32 s47, s31
	s_lshl_b64 s[46:47], s[46:47], 11
	v_lshl_add_u64 v[84:85], v[118:119], 0, s[46:47]
	s_or_b32 s46, s30, 2
	s_mov_b32 s47, s31
	s_lshl_b64 s[46:47], s[46:47], 11
	v_lshl_add_u64 v[86:87], v[118:119], 0, s[46:47]
	s_or_b32 s46, s30, 3
	s_mov_b32 s47, s31
	s_lshl_b64 s[46:47], s[46:47], 11
	v_lshl_add_u64 v[88:89], v[118:119], 0, s[46:47]
	s_or_b32 s46, s30, 16
	s_mov_b32 s47, s31
	s_lshl_b64 s[46:47], s[46:47], 11
	v_lshl_add_u64 v[90:91], v[118:119], 0, s[46:47]
	s_or_b32 s46, s30, 17
	s_mov_b32 s47, s31
	s_lshl_b64 s[46:47], s[46:47], 11
	v_lshl_add_u64 v[92:93], v[118:119], 0, s[46:47]
	s_or_b32 s46, s30, 18
	s_mov_b32 s47, s31
	s_lshl_b64 s[46:47], s[46:47], 11
	v_lshl_add_u64 v[94:95], v[118:119], 0, s[46:47]
	s_or_b32 s46, s30, 19
	s_mov_b32 s47, s31
	s_or_b32 s88, s30, 32
	s_mov_b32 s89, s31
	s_lshl_b64 s[46:47], s[46:47], 11
	s_lshl_b64 s[88:89], s[88:89], 11
	v_lshl_add_u64 v[96:97], v[118:119], 0, s[46:47]
	s_or_b32 s46, s30, 33
	s_mov_b32 s47, s31
	v_lshl_add_u64 v[78:79], v[116:117], 0, s[88:89]
	s_lshl_b64 s[46:47], s[46:47], 11
	global_load_dwordx4 v[74:77], v[74:75], off
	s_nop 0
	global_load_dwordx4 v[78:81], v[78:79], off
	s_nop 0
	global_load_ushort v179, v[82:83], off
	global_load_ushort v180, v[84:85], off
	global_load_ushort v181, v[86:87], off
	global_load_ushort v182, v[88:89], off
	global_load_ushort v183, v[90:91], off
	global_load_ushort v184, v[92:93], off
	global_load_ushort v185, v[94:95], off
	global_load_ushort v186, v[96:97], off
	v_lshl_add_u64 v[84:85], v[118:119], 0, s[46:47]
	s_or_b32 s46, s30, 34
	s_mov_b32 s47, s31
	s_lshl_b64 s[46:47], s[46:47], 11
	v_lshl_add_u64 v[86:87], v[118:119], 0, s[46:47]
	s_or_b32 s46, s30, 35
	s_mov_b32 s47, s31
	s_lshl_b64 s[46:47], s[46:47], 11
	v_lshl_add_u64 v[88:89], v[118:119], 0, s[46:47]
	s_or_b32 s46, s30, 48
	s_mov_b32 s47, s31
	s_lshl_b64 s[46:47], s[46:47], 11
	v_lshl_add_u64 v[90:91], v[118:119], 0, s[46:47]
	s_or_b32 s46, s30, 49
	s_mov_b32 s47, s31
	s_lshl_b64 s[46:47], s[46:47], 11
	v_lshl_add_u64 v[92:93], v[118:119], 0, s[46:47]
	s_or_b32 s46, s30, 50
	s_mov_b32 s47, s31
	s_lshl_b64 s[46:47], s[46:47], 11
	s_or_b32 s30, s30, 51
	v_lshl_add_u64 v[82:83], v[118:119], 0, s[88:89]
	v_lshl_add_u64 v[94:95], v[118:119], 0, s[46:47]
	s_lshl_b64 s[46:47], s[30:31], 11
	v_lshl_add_u64 v[96:97], v[118:119], 0, s[46:47]
	global_load_ushort v187, v[82:83], off
	global_load_ushort v188, v[84:85], off
	global_load_ushort v189, v[86:87], off
	global_load_ushort v190, v[88:89], off
	global_load_ushort v191, v[90:91], off
	global_load_ushort v192, v[92:93], off
	global_load_ushort v193, v[94:95], off
	global_load_ushort v194, v[96:97], off
	s_waitcnt lgkmcnt(0)
	s_barrier
	s_cmp_eq_u32 s37, 64
	s_cbranch_scc1 .Llru_skipw
	ds_read_b128 v[220:223], v219
	ds_read_b128 v[224:227], v219 offset:8704
	s_add_u32 s92, s90, s0
	s_addc_u32 s93, s91, s1
	s_add_u32 s98, s92, 0x20000
	s_addc_u32 s99, s93, 0
	s_waitcnt lgkmcnt(0)
	global_store_dwordx4 v218, v[220:223], s[92:93]
	global_store_dwordx4 v218, v[224:227], s[98:99]
; #define LAS __attribute__((address_space(3)))
; __device__ __forceinline__ v4u pack8(const float* v) { v4u w; w.x = pk2(v[0], v[1]); w.y = pk2(v[2], v[3]); w.z = pk2(v[4], v[5]); w.w = pk2(v[6], v[7]); return w; }
; __device__ __forceinline__ void lru_unit(Frame& F, int seq, int n) {
;     ...
; #pragma unroll
;         for (int p = 0; p < 2; ++p) {
;             const int t = ct + 32 * p;
;             float a[8];
; #pragma unroll
;             for (int e = 0; e < 8; ++e) a[e] = cbias[e];
; #pragma unroll
;             for (int j = 0; j < 4; ++j) {
;                 const int tr = t + j - 3;
;                 const v4u q = (tr >= 0) ? *(const LAS v4u*)(RAW + tr * 136 + 8 * cg) : *(const LAS v4u*)(HALO + (tr + 3) * 136 + 8 * cg);
;                 const float x[8] = {bflo(q.x), bfhi(q.x), bflo(q.y), bfhi(q.y), bflo(q.z), bfhi(q.z), bflo(q.w), bfhi(q.w)};
; #pragma unroll
;                 for (int e = 0; e < 8; ++e) a[e] += x[e] * cw[j][e];
;             }
;             *(LAS f32x4*)(BB + t * 132 + 8 * cg) = (f32x4){a[0], a[1], a[2], a[3]}; *(LAS f32x4*)(BB + t * 132 + 8 * cg + 4) = (f32x4){a[4], a[5], a[6], a[7]};
;             *(LAS v4u*)(XCB + t * 136 + 8 * cg) = pack8(a);
;         }
;         if (tid < 48) *(LAS v4u*)(HALO + (tid >> 4) * 136 + 8 * cg) = *(const LAS v4u*)(RAW + (61 + (tid >> 4)) * 136 + 8 * cg);
.Llru_skipw:
	ds_read_b128 v[82:85], v153
	ds_read_b128 v[86:89], v155
	ds_read_b128 v[90:93], v156
	ds_read_b128 v[94:97], v157
	s_waitcnt lgkmcnt(3)
	v_lshlrev_b32_e32 v98, 16, v82
	v_and_b32_e32 v99, 0xffff0000, v82
	v_lshlrev_b32_e32 v82, 16, v83
	v_and_b32_e32 v83, 0xffff0000, v83
	v_pk_fma_f32 v[98:99], v[14:15], v[98:99], v[10:11]
	s_waitcnt lgkmcnt(2)
	v_lshlrev_b32_e32 v100, 16, v86
	v_and_b32_e32 v101, 0xffff0000, v86
	v_pk_fma_f32 v[82:83], v[16:17], v[82:83], v[12:13]
	v_lshlrev_b32_e32 v86, 16, v87
	v_and_b32_e32 v87, 0xffff0000, v87
	v_pk_fma_f32 v[98:99], v[18:19], v[100:101], v[98:99]
	s_waitcnt lgkmcnt(1)
	v_lshlrev_b32_e32 v100, 16, v90
	v_and_b32_e32 v101, 0xffff0000, v90
	v_pk_fma_f32 v[82:83], v[20:21], v[86:87], v[82:83]
	v_lshlrev_b32_e32 v86, 16, v91
	v_and_b32_e32 v87, 0xffff0000, v91
	v_pk_fma_f32 v[98:99], v[22:23], v[100:101], v[98:99]
	s_waitcnt lgkmcnt(0)
	v_lshlrev_b32_e32 v100, 16, v94
	v_and_b32_e32 v101, 0xffff0000, v94
	v_pk_fma_f32 v[82:83], v[24:25], v[86:87], v[82:83]
	v_lshlrev_b32_e32 v86, 16, v95
	v_and_b32_e32 v87, 0xffff0000, v95
	v_pk_fma_f32 v[98:99], v[34:35], v[100:101], v[98:99]
	v_pk_fma_f32 v[100:101], v[36:37], v[86:87], v[82:83]
	v_lshlrev_b32_e32 v82, 16, v84
	v_and_b32_e32 v83, 0xffff0000, v84
	v_pk_fma_f32 v[82:83], v[6:7], v[82:83], v[2:3]
	v_lshlrev_b32_e32 v86, 16, v88
	v_and_b32_e32 v87, 0xffff0000, v88
	v_pk_fma_f32 v[82:83], v[26:27], v[86:87], v[82:83]
	v_lshlrev_b32_e32 v86, 16, v92
	v_and_b32_e32 v87, 0xffff0000, v92
	v_pk_fma_f32 v[82:83], v[30:31], v[86:87], v[82:83]
	v_lshlrev_b32_e32 v86, 16, v96
	v_and_b32_e32 v87, 0xffff0000, v96
	v_lshlrev_b32_e32 v84, 16, v85
	v_and_b32_e32 v85, 0xffff0000, v85
	v_pk_fma_f32 v[82:83], v[38:39], v[86:87], v[82:83]
	v_pk_fma_f32 v[84:85], v[8:9], v[84:85], v[4:5]
	v_lshlrev_b32_e32 v86, 16, v89
	v_and_b32_e32 v87, 0xffff0000, v89
	v_pk_fma_f32 v[84:85], v[28:29], v[86:87], v[84:85]
	v_lshlrev_b32_e32 v86, 16, v93
	v_and_b32_e32 v87, 0xffff0000, v93
	v_pk_fma_f32 v[84:85], v[32:33], v[86:87], v[84:85]
	v_lshlrev_b32_e32 v86, 16, v97
	v_and_b32_e32 v87, 0xffff0000, v97
	v_pk_fma_f32 v[84:85], v[40:41], v[86:87], v[84:85]
	ds_write_b128 v169, v[98:101] offset:35840
	ds_write_b128 v169, v[82:85] offset:35856
	v_cvt_pk_bf16_f32 v86, v98, v99
	v_cvt_pk_bf16_f32 v87, v100, v101
	v_cvt_pk_bf16_f32 v88, v82, v83
	v_add_u32_e32 v82, v149, v145
	v_cvt_pk_bf16_f32 v89, v84, v85
	ds_write_b128 v82, v[86:89]
	ds_read_b128 v[82:85], v158
	ds_read_b128 v[86:89], v160
	ds_read_b128 v[90:93], v162
	ds_read_b128 v[94:97], v163
	s_waitcnt lgkmcnt(3)
	v_lshlrev_b32_e32 v98, 16, v82
	v_and_b32_e32 v99, 0xffff0000, v82
	v_lshlrev_b32_e32 v82, 16, v83
	v_and_b32_e32 v83, 0xffff0000, v83
	v_pk_fma_f32 v[98:99], v[14:15], v[98:99], v[10:11]
	s_waitcnt lgkmcnt(2)
	v_lshlrev_b32_e32 v100, 16, v86
	v_and_b32_e32 v101, 0xffff0000, v86
	v_pk_fma_f32 v[82:83], v[16:17], v[82:83], v[12:13]
	v_lshlrev_b32_e32 v86, 16, v87
	v_and_b32_e32 v87, 0xffff0000, v87
	v_pk_fma_f32 v[98:99], v[18:19], v[100:101], v[98:99]
	s_waitcnt lgkmcnt(1)
	v_lshlrev_b32_e32 v100, 16, v90
	v_and_b32_e32 v101, 0xffff0000, v90
	v_pk_fma_f32 v[82:83], v[20:21], v[86:87], v[82:83]
	v_lshlrev_b32_e32 v86, 16, v91
	v_and_b32_e32 v87, 0xffff0000, v91
	v_pk_fma_f32 v[98:99], v[22:23], v[100:101], v[98:99]
	s_waitcnt lgkmcnt(0)
	v_lshlrev_b32_e32 v100, 16, v94
	v_and_b32_e32 v101, 0xffff0000, v94
	v_pk_fma_f32 v[82:83], v[24:25], v[86:87], v[82:83]
	v_lshlrev_b32_e32 v86, 16, v95
	v_and_b32_e32 v87, 0xffff0000, v95
	v_pk_fma_f32 v[98:99], v[34:35], v[100:101], v[98:99]
	v_pk_fma_f32 v[100:101], v[36:37], v[86:87], v[82:83]
	v_lshlrev_b32_e32 v82, 16, v84
	v_and_b32_e32 v83, 0xffff0000, v84
	v_pk_fma_f32 v[82:83], v[6:7], v[82:83], v[2:3]
	v_lshlrev_b32_e32 v86, 16, v88
	v_and_b32_e32 v87, 0xffff0000, v88
	v_pk_fma_f32 v[82:83], v[26:27], v[86:87], v[82:83]
	v_lshlrev_b32_e32 v86, 16, v92
	v_and_b32_e32 v87, 0xffff0000, v92
	v_pk_fma_f32 v[82:83], v[30:31], v[86:87], v[82:83]
	v_lshlrev_b32_e32 v86, 16, v96
	v_and_b32_e32 v87, 0xffff0000, v96
	v_lshlrev_b32_e32 v84, 16, v85
	v_and_b32_e32 v85, 0xffff0000, v85
	v_pk_fma_f32 v[82:83], v[38:39], v[86:87], v[82:83]
	v_pk_fma_f32 v[84:85], v[8:9], v[84:85], v[4:5]
	v_lshlrev_b32_e32 v86, 16, v89
	v_and_b32_e32 v87, 0xffff0000, v89
	v_pk_fma_f32 v[84:85], v[28:29], v[86:87], v[84:85]
	v_lshlrev_b32_e32 v86, 16, v93
	v_and_b32_e32 v87, 0xffff0000, v93
	v_pk_fma_f32 v[84:85], v[32:33], v[86:87], v[84:85]
	v_lshlrev_b32_e32 v86, 16, v97
	v_and_b32_e32 v87, 0xffff0000, v97
	v_pk_fma_f32 v[84:85], v[40:41], v[86:87], v[84:85]
	ds_write_b128 v169, v[98:101] offset:52736
	ds_write_b128 v169, v[82:85] offset:52752
	v_cvt_pk_bf16_f32 v86, v98, v99
	v_cvt_pk_bf16_f32 v87, v100, v101
	v_cvt_pk_bf16_f32 v88, v82, v83
	v_add_u32_e32 v82, v149, v151
	v_cvt_pk_bf16_f32 v89, v84, v85
	ds_write_b128 v82, v[86:89]
	s_and_saveexec_b64 s[46:47], s[8:9]
	s_cbranch_execz .LBB0_440
	ds_read_b128 v[82:85], v148 offset:34000
	s_waitcnt lgkmcnt(0)
	ds_write_b128 v148, v[82:85] offset:34816
; #define LAS __attribute__((address_space(3)))
; __device__ __forceinline__ float sigm(float v) { return __builtin_amdgcn_rcpf(1.f + __builtin_amdgcn_exp2f(-LOG2E * v)); }
; __device__ __forceinline__ void lru_unit(Frame& F, int seq, int n) {
;     ...
;         {
;             pg8::f32x4 ar[4], ai_[4];
; #pragma unroll
;             for (int tt = 0; tt < 4; ++tt) { ar[tt] = (pg8::f32x4){0.f, 0.f, 0.f, 0.f}; ai_[tt] = (pg8::f32x4){0.f, 0.f, 0.f, 0.f}; }
; #pragma unroll
;             for (int tt = 0; tt < 4; ++tt)
; #pragma unroll
;                 for (int kk = 0; kk < 4; ++kk) {
;                     const bf16x8 af = *(const LAS bf16x8*)(XCB + (16 * tt + (lane & 15)) * 136 + 32 * kk + 8 * tq);
;                     ar[tt] = __builtin_amdgcn_mfma_f32_16x16x32_bf16(af, Br[kk], ar[tt], 0, 0, 0);
;                     ai_[tt] = __builtin_amdgcn_mfma_f32_16x16x32_bf16(af, Bi[kk], ai_[tt], 0, 0, 0);
;                 }
;             float A[4][4], B[4][4];
; #pragma unroll
;             for (int tt = 0; tt < 4; ++tt)
; #pragma unroll
;                 for (int rg = 0; rg < 4; ++rg) {
;                     const int t = 16 * tt + 4 * tq + rg;
;                     const float r = sigm(ar[tt][rg] + brg), ig = sigm(ai_[tt][rg] + big);
;                     const float av = __builtin_amdgcn_exp2f(r * nsp);
;                     float mult = __builtin_amdgcn_sqrtf(fmaxf(__builtin_fmaf(-av, av, 1.f), 0.f));
;                     if (!smp && (t0 + t) == 0) mult = 1.f;
;                     A[tt][rg] = av; B[tt][rg] = mult * ig * BB[t * 132 + dl];
.LBB0_440:
	s_or_b64 exec, exec, s[46:47]
	s_waitcnt lgkmcnt(0)
	s_barrier
	ds_read_b128 v[82:85], v170
	ds_read_b128 v[90:93], v170 offset:64
	s_waitcnt lgkmcnt(1)
	v_mfma_f32_16x16x32_bf16 v[86:89], v[82:85], v[42:45], 0
	ds_read_b128 v[196:199], v170 offset:13120
	v_mfma_f32_16x16x32_bf16 v[82:85], v[82:85], v[66:69], 0
	s_waitcnt lgkmcnt(1)
	v_mfma_f32_16x16x32_bf16 v[86:89], v[90:93], v[46:49], v[86:89]
	v_mfma_f32_16x16x32_bf16 v[82:85], v[90:93], v[50:53], v[82:85]
	ds_read_b128 v[90:93], v170 offset:128
	s_waitcnt lgkmcnt(0)
	v_mfma_f32_16x16x32_bf16 v[86:89], v[90:93], v[58:61], v[86:89]
	v_mfma_f32_16x16x32_bf16 v[82:85], v[90:93], v[54:57], v[82:85]
	ds_read_b128 v[90:93], v170 offset:192
	s_waitcnt lgkmcnt(0)
	v_mfma_f32_16x16x32_bf16 v[106:109], v[90:93], v[70:73], v[82:85]
	s_nop 4
	ds_read_b128 v[82:85], v170 offset:4352
	s_nop 1
	v_add_f32_e32 v106, v144, v106
	v_mfma_f32_16x16x32_bf16 v[110:113], v[90:93], v[62:65], v[86:89]
	ds_read_b128 v[90:93], v170 offset:4416
	v_mul_f32_e32 v106, 0xbfb8aa3b, v106
	v_exp_f32_e32 v106, v106
	s_waitcnt lgkmcnt(1)
	v_mfma_f32_16x16x32_bf16 v[86:89], v[82:85], v[42:45], 0
	v_add_f32_e32 v107, v144, v107
	s_nop 1
	v_add_f32_e32 v110, v143, v110
	v_mul_f32_e32 v110, 0xbfb8aa3b, v110
	v_mfma_f32_16x16x32_bf16 v[82:85], v[82:85], v[66:69], 0
	v_exp_f32_e32 v110, v110
	v_add_f32_e32 v106, 1.0, v106
	v_rcp_f32_e32 v106, v106
	s_waitcnt lgkmcnt(0)
	v_mfma_f32_16x16x32_bf16 v[86:89], v[90:93], v[46:49], v[86:89]
	v_add_f32_e32 v110, 1.0, v110
	v_rcp_f32_e32 v110, v110
	v_mul_f32_e32 v107, 0xbfb8aa3b, v107
	v_mfma_f32_16x16x32_bf16 v[82:85], v[90:93], v[50:53], v[82:85]
	ds_read_b128 v[90:93], v170 offset:4480
	v_mul_f32_e32 v110, v147, v110
	v_exp_f32_e32 v110, v110
	s_waitcnt lgkmcnt(0)
	v_mfma_f32_16x16x32_bf16 v[86:89], v[90:93], v[58:61], v[86:89]
	v_fma_f32 v195, -v110, v110, 1.0
	v_max_f32_e32 v195, 0, v195
	v_sqrt_f32_e32 v195, v195
	v_mfma_f32_16x16x32_bf16 v[82:85], v[90:93], v[54:57], v[82:85]
	ds_read_b128 v[90:93], v170 offset:4544
	v_exp_f32_e32 v107, v107
	v_add_f32_e32 v109, v144, v109
	s_waitcnt lgkmcnt(0)
	v_mfma_f32_16x16x32_bf16 v[98:101], v[90:93], v[70:73], v[82:85]
	s_nop 2
	ds_read_b128 v[82:85], v170 offset:8704
	v_add_f32_e32 v107, 1.0, v107
	v_rcp_f32_e32 v107, v107
	v_mfma_f32_16x16x32_bf16 v[102:105], v[90:93], v[62:65], v[86:89]
	ds_read_b128 v[90:93], v170 offset:8768
	v_mul_f32_e32 v109, 0xbfb8aa3b, v109
	v_exp_f32_e32 v109, v109
	s_waitcnt lgkmcnt(1)
	v_mfma_f32_16x16x32_bf16 v[86:89], v[82:85], v[42:45], 0
	v_add_f32_e32 v109, 1.0, v109
	s_nop 1
	v_add_f32_e32 v102, v143, v102
	v_mul_f32_e32 v102, 0xbfb8aa3b, v102
	v_mfma_f32_16x16x32_bf16 v[82:85], v[82:85], v[66:69], 0
	v_exp_f32_e32 v102, v102
	v_rcp_f32_e32 v109, v109
	v_add_f32_e32 v98, v144, v98
	s_waitcnt lgkmcnt(0)
	v_mfma_f32_16x16x32_bf16 v[86:89], v[90:93], v[46:49], v[86:89]
	v_add_f32_e32 v102, 1.0, v102
	v_rcp_f32_e32 v102, v102
	v_mul_f32_e32 v98, 0xbfb8aa3b, v98
	v_mfma_f32_16x16x32_bf16 v[82:85], v[90:93], v[50:53], v[82:85]
	ds_read_b128 v[90:93], v170 offset:8832
	v_mul_f32_e32 v102, v147, v102
	v_exp_f32_e32 v98, v98
	s_waitcnt lgkmcnt(0)
	v_mfma_f32_16x16x32_bf16 v[86:89], v[90:93], v[58:61], v[86:89]
	v_add_f32_e32 v98, 1.0, v98
	v_rcp_f32_e32 v98, v98
	v_add_f32_e32 v99, v144, v99
	v_mfma_f32_16x16x32_bf16 v[82:85], v[90:93], v[54:57], v[82:85]
	ds_read_b128 v[90:93], v170 offset:8896
	v_mul_f32_e32 v99, 0xbfb8aa3b, v99
	v_exp_f32_e32 v99, v99
	s_waitcnt lgkmcnt(0)
	v_mfma_f32_16x16x32_bf16 v[94:97], v[90:93], v[62:65], v[86:89]
	v_add_f32_e32 v99, 1.0, v99
	v_rcp_f32_e32 v99, v99
	v_add_f32_e32 v101, v144, v101
	v_mfma_f32_16x16x32_bf16 v[90:93], v[90:93], v[70:73], v[82:85]
	s_nop 3
	v_add_f32_e32 v94, v143, v94
	v_mul_f32_e32 v94, 0xbfb8aa3b, v94
	v_exp_f32_e32 v94, v94
	ds_read_b128 v[82:85], v170 offset:13056
	s_waitcnt lgkmcnt(0)
	v_mfma_f32_16x16x32_bf16 v[86:89], v[82:85], v[42:45], 0
	v_add_f32_e32 v94, 1.0, v94
	v_rcp_f32_e32 v94, v94
	v_add_f32_e32 v90, v144, v90
	v_mfma_f32_16x16x32_bf16 v[82:85], v[82:85], v[66:69], 0
	v_mul_f32_e32 v90, 0xbfb8aa3b, v90
	v_mul_f32_e32 v94, v147, v94
	v_exp_f32_e32 v90, v90
	v_mfma_f32_16x16x32_bf16 v[86:89], v[196:199], v[46:49], v[86:89]
	v_mul_f32_e32 v101, 0xbfb8aa3b, v101
	v_exp_f32_e32 v101, v101
	v_add_f32_e32 v90, 1.0, v90
	v_mfma_f32_16x16x32_bf16 v[82:85], v[196:199], v[50:53], v[82:85]
	ds_read_b128 v[196:199], v170 offset:13184
	v_rcp_f32_e32 v90, v90
	v_add_f32_e32 v101, 1.0, v101
	s_waitcnt lgkmcnt(0)
	v_mfma_f32_16x16x32_bf16 v[86:89], v[196:199], v[58:61], v[86:89]
	v_rcp_f32_e32 v206, v101
	v_add_f32_e32 v91, v144, v91
	v_mul_f32_e32 v91, 0xbfb8aa3b, v91
	v_mfma_f32_16x16x32_bf16 v[82:85], v[196:199], v[54:57], v[82:85]
	ds_read_b128 v[196:199], v170 offset:13248
	v_exp_f32_e32 v91, v91
	v_add_f32_e32 v93, v144, v93
	s_waitcnt lgkmcnt(0)
	v_mfma_f32_16x16x32_bf16 v[86:89], v[196:199], v[62:65], v[86:89]
	v_add_f32_e32 v91, 1.0, v91
	v_rcp_f32_e32 v91, v91
	v_mul_f32_e32 v93, 0xbfb8aa3b, v93
	v_mfma_f32_16x16x32_bf16 v[82:85], v[196:199], v[70:73], v[82:85]
	v_add_u32_e32 v196, s0, v120
	v_cmp_eq_u32_e32 vcc, 0, v196
	s_and_b64 s[46:47], s[40:41], vcc
	v_cndmask_b32_e64 v195, v195, 1.0, s[46:47]
	v_mul_f32_e32 v106, v106, v195
	v_add_u32_e32 v195, 0x8c00, v171
	ds_read2_b32 v[196:197], v195 offset1:132
	v_add_f32_e32 v86, v143, v86
	v_mul_f32_e32 v86, 0xbfb8aa3b, v86
	v_exp_f32_e32 v86, v86
	v_add_f32_e32 v82, v144, v82
	s_waitcnt lgkmcnt(0)
; __device__ __forceinline__ float sigm(float v) { return __builtin_amdgcn_rcpf(1.f + __builtin_amdgcn_exp2f(-LOG2E * v)); }
; __device__ __forceinline__ void lru_unit(Frame& F, int seq, int n) {
;     ...
;             for (int tt = 0; tt < 4; ++tt)
; #pragma unroll
;                 for (int rg = 0; rg < 4; ++rg) {
;                     const int t = 16 * tt + 4 * tq + rg;
;                     const float r = sigm(ar[tt][rg] + brg), ig = sigm(ai_[tt][rg] + big);
;                     const float av = __builtin_amdgcn_exp2f(r * nsp);
;                     float mult = __builtin_amdgcn_sqrtf(fmaxf(__builtin_fmaf(-av, av, 1.f), 0.f));
;                     if (!smp && (t0 + t) == 0) mult = 1.f;
;                     A[tt][rg] = av; B[tt][rg] = mult * ig * BB[t * 132 + dl];
;                 }
; #pragma unroll
;             for (int tt = 0; tt < 4; ++tt)
; #pragma unroll
;                 for (int rg = 1; rg < 4; ++rg) { B[tt][rg] = A[tt][rg] * B[tt][rg - 1] + B[tt][rg]; A[tt][rg] = A[tt][rg] * A[tt][rg - 1]; }
	v_mul_f32_e32 v195, v106, v196
	v_add_f32_e32 v106, v143, v111
	v_mul_f32_e32 v106, 0xbfb8aa3b, v106
	v_exp_f32_e32 v106, v106
	v_add_f32_e32 v86, 1.0, v86
	v_rcp_f32_e32 v86, v86
	v_mul_f32_e32 v82, 0xbfb8aa3b, v82
	v_add_f32_e32 v106, 1.0, v106
	v_rcp_f32_e32 v106, v106
	v_mul_f32_e32 v86, v147, v86
	v_exp_f32_e32 v82, v82
	v_add_f32_e32 v83, v144, v83
	v_mul_f32_e32 v106, v147, v106
	v_exp_f32_e32 v196, v106
	v_add_f32_e32 v82, 1.0, v82
	v_rcp_f32_e32 v82, v82
	v_mul_f32_e32 v83, 0xbfb8aa3b, v83
	v_fma_f32 v106, -v196, v196, 1.0
	v_max_f32_e32 v106, 0, v106
	v_sqrt_f32_e32 v106, v106
	v_exp_f32_e32 v83, v83
	v_exp_f32_e32 v93, v93
	v_add_f32_e32 v92, v144, v92
	v_mul_f32_e32 v106, v107, v106
	v_add_f32_e32 v107, v144, v108
	v_add_f32_e32 v108, v143, v113
	v_mul_f32_e32 v108, 0xbfb8aa3b, v108
	v_exp_f32_e32 v108, v108
	v_mul_f32_e32 v111, v106, v197
	v_add_f32_e32 v106, v143, v112
	v_mul_f32_e32 v106, 0xbfb8aa3b, v106
	v_add_f32_e32 v108, 1.0, v108
	v_rcp_f32_e32 v108, v108
	v_exp_f32_e32 v106, v106
	v_mul_f32_e32 v107, 0xbfb8aa3b, v107
	v_exp_f32_e32 v107, v107
	v_mul_f32_e32 v108, v147, v108
	v_exp_f32_e32 v199, v108
	v_add_f32_e32 v106, 1.0, v106
	v_rcp_f32_e32 v106, v106
	v_add_f32_e32 v83, 1.0, v83
	v_fma_f32 v108, -v199, v199, 1.0
	v_max_f32_e32 v108, 0, v108
	v_sqrt_f32_e32 v108, v108
	v_mul_f32_e32 v106, v147, v106
	v_exp_f32_e32 v197, v106
	v_add_f32_e32 v107, 1.0, v107
	v_mul_f32_e32 v200, v109, v108
	v_exp_f32_e32 v108, v102
	v_fma_f32 v106, -v197, v197, 1.0
	v_max_f32_e32 v106, 0, v106
	v_rcp_f32_e32 v107, v107
	v_fma_f32 v102, -v108, v108, 1.0
	v_max_f32_e32 v102, 0, v102
	v_sqrt_f32_e32 v102, v102
	v_sqrt_f32_e32 v106, v106
	v_fmac_f32_e32 v111, v196, v195
	v_mul_f32_e32 v92, 0xbfb8aa3b, v92
	v_mul_f32_e32 v98, v98, v102
	v_add_u32_e32 v102, 0xac00, v171
	ds_read2_b32 v[112:113], v102 offset0:64 offset1:196
	v_add_f32_e32 v102, v143, v105
	v_mul_f32_e32 v102, 0xbfb8aa3b, v102
	v_exp_f32_e32 v102, v102
	v_mul_f32_e32 v198, v107, v106
	s_waitcnt lgkmcnt(0)
	v_mul_f32_e32 v109, v98, v112
	v_add_f32_e32 v98, v143, v103
	v_mul_f32_e32 v98, 0xbfb8aa3b, v98
	v_exp_f32_e32 v98, v98
	v_add_f32_e32 v102, 1.0, v102
	v_rcp_f32_e32 v102, v102
	v_add_u32_e32 v106, 0x9000, v171
	v_add_f32_e32 v98, 1.0, v98
	v_rcp_f32_e32 v98, v98
	v_mul_f32_e32 v101, v147, v102
	v_exp_f32_e32 v101, v101
	ds_read2_b32 v[106:107], v106 offset0:8 offset1:140
	v_mul_f32_e32 v98, v147, v98
	v_exp_f32_e32 v203, v98
	v_add_f32_e32 v93, 1.0, v93
	v_mul_f32_e32 v201, v197, v111
	v_exp_f32_e32 v92, v92
	v_fma_f32 v98, -v203, v203, 1.0
	v_max_f32_e32 v98, 0, v98
	v_sqrt_f32_e32 v98, v98
	v_rcp_f32_e32 v210, v93
	s_waitcnt lgkmcnt(0)
	v_fmac_f32_e32 v201, v198, v106
	v_mul_f32_e32 v106, v203, v108
	v_mul_f32_e32 v98, v99, v98
	v_mul_f32_e32 v112, v98, v113
	v_add_f32_e32 v98, v143, v104
	v_exp_f32_e32 v104, v94
	v_exp_f32_e32 v113, v86
	v_mul_f32_e32 v98, 0xbfb8aa3b, v98
	v_exp_f32_e32 v98, v98
	v_fma_f32 v94, -v104, v104, 1.0
	v_max_f32_e32 v94, 0, v94
	v_sqrt_f32_e32 v94, v94
	v_fma_f32 v86, -v113, v113, 1.0
	v_max_f32_e32 v86, 0, v86
	v_sqrt_f32_e32 v86, v86
	v_mul_f32_e32 v90, v90, v94
	v_add_u32_e32 v94, 0xce00, v171
	ds_read2_b32 v[102:103], v94 offset1:132
	v_mul_f32_e32 v86, v82, v86
	v_add_u32_e32 v82, 0xee00, v171
	v_add_f32_e32 v98, 1.0, v98
	v_rcp_f32_e32 v98, v98
	s_waitcnt lgkmcnt(0)
	v_mul_f32_e32 v105, v90, v102
	v_add_f32_e32 v90, v143, v95
	v_mul_f32_e32 v90, 0xbfb8aa3b, v90
	v_exp_f32_e32 v90, v90
	v_add_f32_e32 v99, v144, v100
	v_mul_f32_e32 v98, v147, v98
	v_mul_f32_e32 v99, 0xbfb8aa3b, v99
	v_add_f32_e32 v90, 1.0, v90
	v_rcp_f32_e32 v90, v90
	v_exp_f32_e32 v100, v98
	v_exp_f32_e32 v99, v99
	v_fmac_f32_e32 v112, v203, v109
	v_mul_f32_e32 v90, v147, v90
	v_exp_f32_e32 v90, v90
	v_fma_f32 v98, -v100, v100, 1.0
	v_add_f32_e32 v99, 1.0, v99
	v_max_f32_e32 v98, 0, v98
	v_fma_f32 v94, -v90, v90, 1.0
	v_max_f32_e32 v94, 0, v94
	v_sqrt_f32_e32 v94, v94
	v_rcp_f32_e32 v99, v99
	v_sqrt_f32_e32 v98, v98
	v_add_f32_e32 v92, 1.0, v92
	v_mul_f32_e32 v91, v91, v94
	v_add_f32_e32 v94, v143, v96
	v_mul_f32_e32 v94, 0xbfb8aa3b, v94
	v_exp_f32_e32 v94, v94
	v_mul_f32_e32 v91, v91, v103
	v_mul_f32_e32 v205, v99, v98
	v_add_u32_e32 v98, 0xb000, v171
	v_add_f32_e32 v94, 1.0, v94
	v_rcp_f32_e32 v94, v94
	ds_read2_b32 v[98:99], v98 offset0:72 offset1:204
	v_rcp_f32_e32 v92, v92
	v_fmac_f32_e32 v91, v90, v105
	v_mul_f32_e32 v94, v147, v94
	v_exp_f32_e32 v95, v94
	v_add_u32_e32 v94, 0xd200, v171
	ds_read2_b32 v[102:103], v94 offset0:8 offset1:140
	v_add_f32_e32 v94, v143, v97
	ds_read2_b32 v[96:97], v82 offset0:64 offset1:196
	v_add_f32_e32 v82, v143, v87
	v_mul_f32_e32 v82, 0xbfb8aa3b, v82
	v_exp_f32_e32 v82, v82
	v_rcp_f32_e32 v87, v83
	v_add_f32_e32 v83, v144, v84
	v_mul_f32_e32 v83, 0xbfb8aa3b, v83
	v_add_f32_e32 v82, 1.0, v82
	v_rcp_f32_e32 v82, v82
	v_exp_f32_e32 v83, v83
	v_mul_f32_e32 v94, 0xbfb8aa3b, v94
	v_exp_f32_e32 v94, v94
	v_mul_f32_e32 v82, v147, v82
	v_exp_f32_e32 v204, v82
	v_add_f32_e32 v82, v143, v88
	v_mul_f32_e32 v82, 0xbfb8aa3b, v82
	v_exp_f32_e32 v82, v82
	v_add_f32_e32 v83, 1.0, v83
	v_rcp_f32_e32 v214, v83
	v_add_f32_e32 v83, v144, v85
	v_add_f32_e32 v82, 1.0, v82
	v_rcp_f32_e32 v82, v82
	v_mul_f32_e32 v83, 0xbfb8aa3b, v83
	v_add_f32_e32 v94, 1.0, v94
	v_exp_f32_e32 v83, v83
	v_mul_f32_e32 v82, v147, v82
	v_exp_f32_e32 v207, v82
	v_add_u32_e32 v82, 0xf200, v171
	ds_read2_b32 v[208:209], v82 offset0:72 offset1:204
	v_add_f32_e32 v82, v143, v89
	v_mul_f32_e32 v82, 0xbfb8aa3b, v82
	v_exp_f32_e32 v82, v82
	v_rcp_f32_e32 v94, v94
	v_add_f32_e32 v83, 1.0, v83
	v_rcp_f32_e32 v215, v83
	v_add_f32_e32 v82, 1.0, v82
	v_rcp_f32_e32 v82, v82
	v_mul_f32_e32 v93, v147, v94
	v_mul_f32_e32 v83, v100, v112
	v_exp_f32_e32 v93, v93
	v_mul_f32_e32 v82, v147, v82
	v_exp_f32_e32 v211, v82
	v_fma_f32 v82, -v101, v101, 1.0
	v_max_f32_e32 v82, 0, v82
	v_sqrt_f32_e32 v82, v82
	s_waitcnt lgkmcnt(3)
; #define GAS __attribute__((address_space(1)))
; __device__ __forceinline__ unsigned pk2(float lo, float hi) { return pg8::cvt_pk_bf16(lo, hi); }
; __device__ __forceinline__ void lru_unit(Frame& F, int seq, int n) {
;     ...
;             float EA[4], EB[4], TA[4], TB[4];
; #pragma unroll
;             for (int tt = 0; tt < 4; ++tt) {
;                 float SA = A[tt][3], SB = B[tt][3];
;                 { const float pA = __shfl_up(SA, 16), pB = __shfl_up(SB, 16); if (tq >= 1) { SB = SA * pB + SB; SA = SA * pA; } }
;                 { const float pA = __shfl_up(SA, 32), pB = __shfl_up(SB, 32); if (tq >= 2) { SB = SA * pB + SB; SA = SA * pA; } }
;                 { const float pA = __shfl_up(SA, 16), pB = __shfl_up(SB, 16); EA[tt] = (tq >= 1) ? pA : 1.f; EB[tt] = (tq >= 1) ? pB : 0.f; }
;                 TA[tt] = __shfl(SA, (lane & 15) + 48); TB[tt] = __shfl(SB, (lane & 15) + 48);
;             }
;             const size_t r0 = rowbase + t0 + 4 * tq;
; #pragma unroll
;             for (int tt = 0; tt < 4; ++tt) {
;                 const float hin = EA[tt] * hc + EB[tt];
; #pragma unroll
;                 for (int rg = 0; rg < 4; ++rg) { const float h = A[tt][rg] * hin + B[tt][rg];
;                     const float y = h * bf2f(zc[4 * tt + rg]);
;                     *(GAS unsigned short*)(YAB + (r0 + 16 * tt + rg) * (2 * DM) + dg) = (unsigned short)(pk2(y, 0.f) & 0xffffu); }
;                 hc = TA[tt] * hc + TB[tt];
	v_fmac_f32_e32 v83, v205, v98
	v_mul_f32_e32 v98, v100, v106
	v_mov_b32_e32 v100, v99
	v_mul_f32_e32 v82, v206, v82
	v_pk_mul_f32 v[84:85], v[82:83], v[100:101]
	v_fma_f32 v88, -v93, v93, 1.0
	v_add_f32_e32 v99, v84, v85
	v_fma_f32 v84, -v95, v95, 1.0
	v_max_f32_e32 v84, 0, v84
	v_sqrt_f32_e32 v84, v84
	v_max_f32_e32 v88, 0, v88
	v_sqrt_f32_e32 v88, v88
	v_mul_f32_e32 v82, v90, v104
	s_waitcnt lgkmcnt(2)
	v_mov_b32_e32 v94, v102
	v_mul_f32_e32 v90, v92, v84
	v_mul_f32_e32 v84, v91, v95
	v_pk_fma_f32 v[84:85], v[90:91], v[94:95], v[84:85] op_sel_hi:[1,1,0]
	v_mov_b32_e32 v92, v103
	v_mul_f32_e32 v88, v210, v88
	v_mov_b32_e32 v89, v84
	v_pk_mul_f32 v[88:89], v[88:89], v[92:93]
	s_waitcnt lgkmcnt(1)
	v_mov_b32_e32 v205, v97
	v_add_f32_e32 v90, v88, v89
	v_fma_f32 v88, -v204, v204, 1.0
	v_max_f32_e32 v88, 0, v88
	v_sqrt_f32_e32 v89, v88
	v_mov_b32_e32 v88, v96
	v_mul_f32_e32 v85, v95, v82
	v_mul_f32_e32 v94, v93, v85
	v_pk_mul_f32 v[88:89], v[86:87], v[88:89]
	s_waitcnt lgkmcnt(0)
	v_mov_b32_e32 v206, v208
	v_mul_f32_e32 v86, v97, v89
	v_pk_fma_f32 v[86:87], v[204:205], v[88:89], v[86:87] op_sel_hi:[1,1,0]
	v_fma_f32 v89, -v207, v207, 1.0
	v_max_f32_e32 v89, 0, v89
	v_sqrt_f32_e32 v89, v89
	v_mov_b32_e32 v93, v86
	v_mul_f32_e32 v96, v86, v207
	v_mul_f32_e32 v202, v196, v110
	v_mul_f32_e32 v92, v214, v89
	v_pk_fma_f32 v[92:93], v[92:93], v[206:207], v[96:97] op_sel_hi:[1,1,0]
	v_mul_f32_e32 v197, v197, v202
	v_fma_f32 v93, -v211, v211, 1.0
	v_max_f32_e32 v93, 0, v93
	v_sqrt_f32_e32 v93, v93
	v_mul_f32_e32 v196, v199, v201
	v_mov_b32_e32 v210, v209
	v_mov_b32_e32 v97, v92
	v_mul_f32_e32 v96, v215, v93
	v_fmac_f32_e32 v196, v200, v107
	v_mul_f32_e32 v107, v199, v197
	v_pk_mul_f32 v[96:97], v[96:97], v[210:211]
	v_mul_f32_e32 v100, v101, v98
	v_add_f32_e32 v93, v96, v97
	ds_bpermute_b32 v96, v124, v107
	ds_bpermute_b32 v97, v124, v196
	v_mul_f32_e32 v87, v204, v113
	v_mul_f32_e32 v89, v207, v87
	v_mul_f32_e32 v95, v211, v89
	s_waitcnt lgkmcnt(1)
	v_mul_f32_e32 v96, v107, v96
	s_waitcnt lgkmcnt(0)
	v_fma_f32 v97, v107, v97, v196
	v_cndmask_b32_e64 v96, v96, v107, s[4:5]
	v_cndmask_b32_e64 v97, v97, v196, s[4:5]
	ds_bpermute_b32 v101, v125, v96
	ds_bpermute_b32 v102, v125, v97
	s_waitcnt lgkmcnt(1)
	v_mul_f32_e32 v101, v96, v101
	s_waitcnt lgkmcnt(0)
	v_fma_f32 v102, v96, v102, v97
	v_cndmask_b32_e64 v96, v96, v101, s[6:7]
	v_cndmask_b32_e64 v97, v97, v102, s[6:7]
	ds_bpermute_b32 v101, v124, v96
	ds_bpermute_b32 v199, v164, v96
	ds_bpermute_b32 v96, v124, v100
	ds_bpermute_b32 v102, v124, v97
	ds_bpermute_b32 v200, v164, v97
	ds_bpermute_b32 v97, v124, v99
	s_waitcnt lgkmcnt(5)
	v_cndmask_b32_e64 v101, v101, 1.0, s[4:5]
	s_waitcnt lgkmcnt(3)
	v_mul_f32_e32 v96, v100, v96
	v_cndmask_b32_e64 v96, v96, v100, s[4:5]
	s_waitcnt lgkmcnt(2)
	v_cndmask_b32_e64 v198, v102, 0, s[4:5]
	s_waitcnt lgkmcnt(0)
	v_fma_f32 v97, v100, v97, v99
	v_cndmask_b32_e64 v97, v97, v99, s[4:5]
	ds_bpermute_b32 v102, v125, v96
	ds_bpermute_b32 v103, v125, v97
	v_fmac_f32_e32 v198, v146, v101
	v_fmac_f32_e32 v195, v110, v198
	v_fmac_f32_e32 v111, v202, v198
	s_waitcnt lgkmcnt(1)
	v_mul_f32_e32 v102, v96, v102
	s_waitcnt lgkmcnt(0)
	v_fma_f32 v103, v96, v103, v97
	v_cndmask_b32_e64 v96, v96, v102, s[6:7]
	v_cndmask_b32_e64 v97, v97, v103, s[6:7]
	ds_bpermute_b32 v102, v124, v96
	ds_bpermute_b32 v205, v164, v96
	ds_bpermute_b32 v96, v124, v94
	ds_bpermute_b32 v103, v124, v97
	ds_bpermute_b32 v206, v164, v97
	ds_bpermute_b32 v97, v124, v90
	s_waitcnt lgkmcnt(5)
	v_cndmask_b32_e64 v203, v102, 1.0, s[4:5]
	s_waitcnt lgkmcnt(3)
	v_mul_f32_e32 v96, v94, v96
	v_cndmask_b32_e64 v96, v96, v94, s[4:5]
	ds_bpermute_b32 v102, v125, v96
	s_waitcnt lgkmcnt(1)
	v_fma_f32 v97, v94, v97, v90
	v_cndmask_b32_e64 v97, v97, v90, s[4:5]
	v_cndmask_b32_e64 v204, v103, 0, s[4:5]
	ds_bpermute_b32 v103, v125, v97
	s_waitcnt lgkmcnt(1)
	v_mul_f32_e32 v102, v96, v102
	v_fmac_f32_e32 v201, v197, v198
	v_fmac_f32_e32 v196, v107, v198
	v_fmac_f32_e32 v200, v146, v199
	s_waitcnt lgkmcnt(0)
	v_fma_f32 v103, v96, v103, v97
	v_cndmask_b32_e64 v96, v96, v102, s[6:7]
	v_cndmask_b32_e64 v97, v97, v103, s[6:7]
	ds_bpermute_b32 v102, v124, v96
	ds_bpermute_b32 v209, v164, v96
	ds_bpermute_b32 v96, v124, v95
	ds_bpermute_b32 v103, v124, v97
	ds_bpermute_b32 v210, v164, v97
	ds_bpermute_b32 v97, v124, v93
	s_waitcnt lgkmcnt(5)
	v_cndmask_b32_e64 v207, v102, 1.0, s[4:5]
	s_waitcnt lgkmcnt(3)
	v_mul_f32_e32 v96, v95, v96
	v_cndmask_b32_e64 v96, v96, v95, s[4:5]
	ds_bpermute_b32 v102, v125, v96
	s_waitcnt lgkmcnt(1)
	v_fma_f32 v97, v95, v97, v93
	v_cndmask_b32_e64 v97, v97, v93, s[4:5]
	v_cndmask_b32_e64 v208, v103, 0, s[4:5]
	ds_bpermute_b32 v103, v125, v97
	s_waitcnt lgkmcnt(1)
	v_mul_f32_e32 v102, v96, v102
	v_fmac_f32_e32 v204, v200, v203
	v_fmac_f32_e32 v109, v108, v204
	v_fmac_f32_e32 v112, v106, v204
	s_waitcnt lgkmcnt(0)
	v_fma_f32 v103, v96, v103, v97
	v_cndmask_b32_e64 v96, v96, v102, s[6:7]
	v_cndmask_b32_e64 v97, v97, v103, s[6:7]
	ds_bpermute_b32 v102, v124, v96
	ds_bpermute_b32 v103, v124, v97
	ds_bpermute_b32 v215, v164, v96
	v_lshlrev_b32_e32 v96, 16, v176
	v_mul_f32_e32 v96, v195, v96
	ds_bpermute_b32 v216, v164, v97
	v_cvt_pk_bf16_f32 v101, v96, v115
	v_lshl_add_u64 v[96:97], v[122:123], 0, s[0:1]
	s_waitcnt lgkmcnt(3)
; #define GAS __attribute__((address_space(1)))
; __device__ __forceinline__ unsigned pk2(float lo, float hi) { return pg8::cvt_pk_bf16(lo, hi); }
; __device__ __forceinline__ void lru_unit(Frame& F, int seq, int n) {
;     ...
;             const size_t r0 = rowbase + t0 + 4 * tq;
; #pragma unroll
;             for (int tt = 0; tt < 4; ++tt) {
;                 const float hin = EA[tt] * hc + EB[tt];
; #pragma unroll
;                 for (int rg = 0; rg < 4; ++rg) { const float h = A[tt][rg] * hin + B[tt][rg];
;                     const float y = h * bf2f(zc[4 * tt + rg]);
;                     *(GAS unsigned short*)(YAB + (r0 + 16 * tt + rg) * (2 * DM) + dg) = (unsigned short)(pk2(y, 0.f) & 0xffffu); }
;                 hc = TA[tt] * hc + TB[tt];
;             }
; #pragma unroll
;             for (int i = 0; i < 16; ++i) zc[i] = zn[i];
	v_cndmask_b32_e64 v211, v102, 1.0, s[4:5]
	v_add_co_u32_e32 v102, vcc, s77, v96
	s_waitcnt lgkmcnt(2)
	v_cndmask_b32_e64 v214, v103, 0, s[4:5]
	v_addc_co_u32_e32 v103, vcc, 0, v97, vcc
	ds_write_b16 v217, v101 offset:0
	v_lshlrev_b32_e32 v101, 16, v173
	v_mul_f32_e32 v101, v111, v101
	v_cvt_pk_bf16_f32 v101, v101, v115
	ds_write_b16 v217, v101 offset:272
	s_waitcnt vmcnt(31)
	v_lshlrev_b32_e32 v101, 16, v177
	v_mul_f32_e32 v101, v201, v101
	v_add_co_u32_e32 v102, vcc, s78, v96
	v_cvt_pk_bf16_f32 v101, v101, v115
	v_fmac_f32_e32 v83, v98, v204
	s_nop 0
	v_addc_co_u32_e32 v103, vcc, 0, v97, vcc
	ds_write_b16 v217, v101 offset:544
	s_waitcnt vmcnt(30)
	v_lshlrev_b32_e32 v101, 16, v174
	v_mul_f32_e32 v101, v196, v101
	v_cvt_pk_bf16_f32 v101, v101, v115
	ds_write_b16 v217, v101 offset:816
	s_waitcnt vmcnt(28)
	v_lshlrev_b32_e32 v101, 16, v178
	v_mul_f32_e32 v101, v109, v101
	v_add_co_u32_e32 v102, vcc, s79, v96
	v_cvt_pk_bf16_f32 v101, v101, v115
	s_waitcnt vmcnt(27)
	v_lshlrev_b32_e32 v98, 16, v175
	v_addc_co_u32_e32 v103, vcc, 0, v97, vcc
	ds_write_b16 v217, v101 offset:4352
	v_lshlrev_b32_e32 v101, 16, v167
	v_mul_f32_e32 v101, v112, v101
	v_cvt_pk_bf16_f32 v101, v101, v115
	ds_write_b16 v217, v101 offset:4624
	v_mul_f32_e32 v83, v83, v98
	v_add_co_u32_e32 v102, vcc, s80, v96
	v_cvt_pk_bf16_f32 v83, v83, v115
	v_fmac_f32_e32 v99, v100, v204
	s_nop 0
	v_addc_co_u32_e32 v103, vcc, 0, v97, vcc
	ds_write_b16 v217, v83 offset:4896
	s_waitcnt vmcnt(26)
	v_lshlrev_b32_e32 v83, 16, v172
	v_mul_f32_e32 v83, v99, v83
	v_fmac_f32_e32 v206, v200, v205
	v_cvt_pk_bf16_f32 v83, v83, v115
	v_fmac_f32_e32 v208, v206, v207
	ds_write_b16 v217, v83 offset:5168
	v_fmac_f32_e32 v105, v104, v208
	s_waitcnt vmcnt(25)
	v_lshlrev_b32_e32 v83, 16, v168
	v_add_co_u32_e32 v98, vcc, s81, v96
	v_fmac_f32_e32 v91, v82, v208
	s_waitcnt vmcnt(24)
	v_lshlrev_b32_e32 v82, 16, v166
	v_mul_f32_e32 v83, v105, v83
	v_addc_co_u32_e32 v99, vcc, 0, v97, vcc
	v_mul_f32_e32 v82, v91, v82
	v_cvt_pk_bf16_f32 v83, v83, v115
	ds_write_b16 v217, v83 offset:8704
	v_cvt_pk_bf16_f32 v82, v82, v115
	ds_write_b16 v217, v82 offset:8976
	v_fmac_f32_e32 v84, v85, v208
	s_waitcnt vmcnt(23)
	v_lshlrev_b32_e32 v82, 16, v165
	v_mul_f32_e32 v82, v84, v82
	v_cvt_pk_bf16_f32 v84, v82, v115
	v_add_co_u32_e32 v82, vcc, s82, v96
	v_fmac_f32_e32 v90, v94, v208
	s_nop 0
	v_addc_co_u32_e32 v83, vcc, 0, v97, vcc
	ds_write_b16 v217, v84 offset:9248
	s_waitcnt vmcnt(22)
	v_lshlrev_b32_e32 v84, 16, v161
	v_fmac_f32_e32 v210, v206, v209
	v_mul_f32_e32 v84, v90, v84
	v_fmac_f32_e32 v214, v210, v211
	v_cvt_pk_bf16_f32 v84, v84, v115
	ds_write_b16 v217, v84 offset:9520
	v_fmac_f32_e32 v88, v113, v214
	s_waitcnt vmcnt(20)
	v_lshlrev_b32_e32 v82, 16, v159
	v_mul_f32_e32 v82, v88, v82
	v_cvt_pk_bf16_f32 v84, v82, v115
	v_add_co_u32_e32 v82, vcc, s83, v96
	v_fmac_f32_e32 v86, v87, v214
	s_nop 0
	v_addc_co_u32_e32 v83, vcc, 0, v97, vcc
	ds_write_b16 v217, v84 offset:13056
	v_lshlrev_b32_e32 v84, 16, v154
	v_mul_f32_e32 v84, v86, v84
	v_cvt_pk_bf16_f32 v84, v84, v115
	ds_write_b16 v217, v84 offset:13328
	v_fmac_f32_e32 v92, v89, v214
	s_waitcnt vmcnt(19)
	v_lshlrev_b32_e32 v82, 16, v152
	v_mul_f32_e32 v82, v92, v82
	v_cvt_pk_bf16_f32 v84, v82, v115
	v_add_co_u32_e32 v82, vcc, s84, v96
	v_fmac_f32_e32 v93, v95, v214
	s_nop 0
	v_addc_co_u32_e32 v83, vcc, 0, v97, vcc
	ds_write_b16 v217, v84 offset:13600
	s_waitcnt vmcnt(18)
	v_lshlrev_b32_e32 v82, 16, v150
	v_mul_f32_e32 v82, v93, v82
	v_cvt_pk_bf16_f32 v84, v82, v115
	v_add_co_u32_e32 v82, vcc, 0x4c433000, v96
	s_waitcnt lgkmcnt(0)
	v_mov_b32_e32 v146, v216
	v_addc_co_u32_e32 v83, vcc, 0, v97, vcc
	s_add_u32 s0, s0, 0x40000
	v_fmac_f32_e32 v146, v210, v215
	s_addc_u32 s1, s1, 0
	s_and_b64 vcc, exec, s[44:45]
	ds_write_b16 v217, v84 offset:13872
	s_cbranch_vccnz .LBB0_442
	s_waitcnt vmcnt(15)
	v_mov_b32_e32 v176, v179
	s_waitcnt vmcnt(14)
	v_mov_b32_e32 v173, v180
	s_waitcnt vmcnt(13)
	v_mov_b32_e32 v177, v181
	s_waitcnt vmcnt(12)
	v_mov_b32_e32 v174, v182
	s_waitcnt vmcnt(11)
	v_mov_b32_e32 v178, v183
	s_waitcnt vmcnt(10)
	v_mov_b32_e32 v167, v184
	s_waitcnt vmcnt(9)
	v_mov_b32_e32 v175, v185
	s_waitcnt vmcnt(8)
	v_mov_b32_e32 v172, v186
	s_waitcnt vmcnt(7)
	v_mov_b32_e32 v168, v187
	s_waitcnt vmcnt(6)
	v_mov_b32_e32 v166, v188
	s_waitcnt vmcnt(5)
	v_mov_b32_e32 v165, v189
	s_waitcnt vmcnt(4)
	v_mov_b32_e32 v161, v190
	s_waitcnt vmcnt(3)
	v_mov_b32_e32 v159, v191
	s_waitcnt vmcnt(2)
	v_mov_b32_e32 v154, v192
	s_waitcnt vmcnt(1)
	v_mov_b32_e32 v152, v193
	s_waitcnt vmcnt(0)
	v_mov_b32_e32 v150, v194
	s_branch .LBB0_438
.LBB0_442:
	s_add_u32 s92, s90, s0
	s_addc_u32 s93, s91, s1
	s_and_saveexec_b64 s[0:1], s[4:5]
	s_cbranch_execz .LBB0_424
	s_and_b64 s[4:5], exec, s[40:41]
	s_cselect_b32 s4, s36, s42
	s_cselect_b32 s2, s85, 0x318e0000
	s_ashr_i32 s5, s4, 31
	s_add_u32 s2, s72, s2
	s_addc_u32 s6, s73, 0
	s_lshl_b64 s[4:5], s[4:5], 12
	s_add_u32 s4, s2, s4
	s_addc_u32 s5, s6, s5
	v_lshl_add_u64 v[2:3], v[114:115], 2, s[4:5]
	global_store_dword v[2:3], v146, off
	s_branch .LBB0_424
